# adaLN partial units: silu computed once per lane and broadcast by v_readlane, 16 weight rows in flight (was 3 IEEE divisions per k per lane, <=3 loads in flight)
# speedup vs baseline: 1.0317x; 1.0317x over previous
.LBB0_701:
	s_andn2_b64 vcc, exec, s[0:1]
	s_cbranch_vccnz .LBB0_582
	s_lshl_b32 s0, s5, 2
	v_add_u32_e32 v37, s0, v51
	s_mov_b32 s1, 0x2aaaaaab
	v_mul_hi_i32 v1, v37, s1
	v_lshrrev_b32_e32 v2, 31, v1
	v_ashrrev_i32_e32 v1, 6, v1
	v_lshrrev_b32_e32 v0, 6, v36
	v_add_u32_e32 v54, v1, v2
	v_mul_i32_i24_e32 v1, 0xfffffe80, v54
	v_add_u16_e32 v0, s0, v0
	v_add_lshl_u32 v1, v1, v37, 4
	s_movk_i32 s1, 0xff00
	v_and_b32_e32 v0, 15, v0
	v_and_or_b32 v40, v1, s1, v52
	v_lshlrev_b32_e32 v192, 8, v0
	v_mul_hi_u32_u24_e32 v1, 0x180000, v0
	v_mul_u32_u24_e32 v0, 0x180000, v0
	s_mov_b32 s0, 0x1800000
	v_ashrrev_i32_e32 v41, 31, v40
	v_readlane_b32 s40, v253, 56
	v_mad_i64_i32 v[0:1], s[0:1], v54, s0, v[0:1]
	v_readlane_b32 s42, v253, 58
	v_readlane_b32 s43, v253, 59
	v_readlane_b32 s46, v253, 62
	v_readlane_b32 s47, v253, 63
	v_lshl_add_u64 v[0:1], v[40:41], 2, v[0:1]
	v_mov_b32_e32 v4, 0
	v_lshl_add_u64 v[42:43], s[42:43], 0, v[192:193]
	v_lshl_add_u64 v[44:45], s[46:47], 0, v[192:193]
	v_lshl_add_u64 v[46:47], s[60:61], 0, v[0:1]
	s_mov_b64 s[0:1], 0
	v_mov_b32_e32 v5, v4
	v_mov_b32_e32 v6, v4
	v_mov_b32_e32 v7, v4
	v_mov_b32_e32 v8, v4
	v_mov_b32_e32 v9, v4
	v_mov_b32_e32 v10, v4
	v_mov_b32_e32 v11, v4
	v_mov_b32_e32 v0, v4
	v_mov_b32_e32 v1, v4
	v_mov_b32_e32 v2, v4
	v_mov_b32_e32 v3, v4
	v_readlane_b32 s41, v253, 57
	v_readlane_b32 s44, v253, 60
	v_readlane_b32 s45, v253, 61
	v_readlane_b32 s48, v254, 0
	v_readlane_b32 s49, v254, 1
	v_readlane_b32 s50, v254, 2
	v_readlane_b32 s51, v254, 3
	v_readlane_b32 s52, v254, 4
	v_readlane_b32 s53, v254, 5
	v_readlane_b32 s54, v254, 6
	v_readlane_b32 s55, v254, 7
	v_lshlrev_b32_e32 v62, 2, v223
	v_mov_b32_e32 v63, 0
	v_lshl_add_u64 v[60:61], v[42:43], 0, v[62:63]
	global_load_dword v70, v[60:61], off
	v_add_co_u32_e32 v64, vcc, 0x1000, v60
	s_nop 0
	v_addc_co_u32_e32 v65, vcc, 0, v61, vcc
	global_load_dword v71, v[64:65], off
	v_lshl_add_u64 v[60:61], v[44:45], 0, v[62:63]
	global_load_dword v72, v[60:61], off
	v_add_co_u32_e32 v66, vcc, 0xfffe8000, v46
	s_nop 0
	v_addc_co_u32_e32 v67, vcc, -1, v47, vcc
	s_nop 0
	v_readfirstlane_b32 s0, v66
	v_readfirstlane_b32 s1, v67
	s_nop 0
	v_subrev_u32_e32 v68, s0, v66
	s_nop 4
	global_load_dwordx4 v[84:87], v68, s[0:1] nt
	s_add_u32 s0, s0, 0x6000
	s_addc_u32 s1, s1, 0
	global_load_dwordx4 v[88:91], v68, s[0:1] nt
	s_add_u32 s0, s0, 0x6000
	s_addc_u32 s1, s1, 0
	global_load_dwordx4 v[92:95], v68, s[0:1] nt
	s_add_u32 s0, s0, 0x6000
	s_addc_u32 s1, s1, 0
	global_load_dwordx4 v[96:99], v68, s[0:1] nt
	s_add_u32 s0, s0, 0x6000
	s_addc_u32 s1, s1, 0
	global_load_dwordx4 v[100:103], v68, s[0:1] nt
	s_add_u32 s0, s0, 0x6000
	s_addc_u32 s1, s1, 0
	global_load_dwordx4 v[104:107], v68, s[0:1] nt
	s_add_u32 s0, s0, 0x6000
	s_addc_u32 s1, s1, 0
	global_load_dwordx4 v[108:111], v68, s[0:1] nt
	s_add_u32 s0, s0, 0x6000
	s_addc_u32 s1, s1, 0
	global_load_dwordx4 v[112:115], v68, s[0:1] nt
	s_add_u32 s0, s0, 0x6000
	s_addc_u32 s1, s1, 0
	global_load_dwordx4 v[128:131], v68, s[0:1] nt
	s_add_u32 s0, s0, 0x6000
	s_addc_u32 s1, s1, 0
	global_load_dwordx4 v[132:135], v68, s[0:1] nt
	s_add_u32 s0, s0, 0x6000
	s_addc_u32 s1, s1, 0
	global_load_dwordx4 v[136:139], v68, s[0:1] nt
	s_add_u32 s0, s0, 0x6000
	s_addc_u32 s1, s1, 0
	global_load_dwordx4 v[140:143], v68, s[0:1] nt
	s_add_u32 s0, s0, 0x6000
	s_addc_u32 s1, s1, 0
	global_load_dwordx4 v[144:147], v68, s[0:1] nt
	s_add_u32 s0, s0, 0x6000
	s_addc_u32 s1, s1, 0
	global_load_dwordx4 v[148:151], v68, s[0:1] nt
	s_add_u32 s0, s0, 0x6000
	s_addc_u32 s1, s1, 0
	global_load_dwordx4 v[152:155], v68, s[0:1] nt
	s_add_u32 s0, s0, 0x6000
	s_addc_u32 s1, s1, 0
	global_load_dwordx4 v[156:159], v68, s[0:1] nt
	s_add_u32 s0, s0, 0x6000
	s_addc_u32 s1, s1, 0
	s_waitcnt vmcnt(16)
	v_mul_f32_e32 v76, 0xbfb8aa3b, v70
	v_exp_f32_e32 v76, v76
	s_nop 0
	v_add_f32_e32 v76, 1.0, v76
	v_div_scale_f32 v77, s[2:3], v76, v76, v70
	v_rcp_f32_e32 v78, v77
	s_nop 0
	v_fma_f32 v79, -v77, v78, 1.0
	v_fmac_f32_e32 v78, v79, v78
	v_div_scale_f32 v79, vcc, v70, v76, v70
	v_mul_f32_e32 v80, v79, v78
	v_fma_f32 v81, -v77, v80, v79
	v_fmac_f32_e32 v80, v81, v78
	v_fma_f32 v77, -v77, v80, v79
	v_div_fmas_f32 v77, v77, v78, v80
	v_div_fixup_f32 v73, v77, v76, v70
	v_mul_f32_e32 v76, 0xbfb8aa3b, v71
	v_exp_f32_e32 v76, v76
	s_nop 0
	v_add_f32_e32 v76, 1.0, v76
	v_div_scale_f32 v77, s[2:3], v76, v76, v71
	v_rcp_f32_e32 v78, v77
	s_nop 0
	v_fma_f32 v79, -v77, v78, 1.0
	v_fmac_f32_e32 v78, v79, v78
	v_div_scale_f32 v79, vcc, v71, v76, v71
	v_mul_f32_e32 v80, v79, v78
	v_fma_f32 v81, -v77, v80, v79
	v_fmac_f32_e32 v80, v81, v78
	v_fma_f32 v77, -v77, v80, v79
	v_div_fmas_f32 v77, v77, v78, v80
	v_div_fixup_f32 v74, v77, v76, v71
	v_mul_f32_e32 v76, 0xbfb8aa3b, v72
	v_exp_f32_e32 v76, v76
	s_nop 0
	v_add_f32_e32 v76, 1.0, v76
	v_div_scale_f32 v77, s[2:3], v76, v76, v72
	v_rcp_f32_e32 v78, v77
	s_nop 0
	v_fma_f32 v79, -v77, v78, 1.0
	v_fmac_f32_e32 v78, v79, v78
	v_div_scale_f32 v79, vcc, v72, v76, v72
	v_mul_f32_e32 v80, v79, v78
	v_fma_f32 v81, -v77, v80, v79
	v_fmac_f32_e32 v80, v81, v78
	v_fma_f32 v77, -v77, v80, v79
	v_div_fmas_f32 v77, v77, v78, v80
	v_div_fixup_f32 v75, v77, v76, v72
	s_mov_b32 s2, 0
	s_mov_b32 s3, 3
.Lada_loop:
	s_waitcnt vmcnt(15)
	v_readlane_b32 s8, v73, s2
	v_readlane_b32 s9, v74, s2
	v_readlane_b32 s10, v75, s2
	s_add_i32 s2, s2, 1
	v_fmac_f32_e32 v4, s8, v84
	v_fmac_f32_e32 v5, s8, v85
	v_fmac_f32_e32 v6, s8, v86
	v_fmac_f32_e32 v7, s8, v87
	v_fmac_f32_e32 v8, s9, v84
	v_fmac_f32_e32 v9, s9, v85
	v_fmac_f32_e32 v10, s9, v86
	v_fmac_f32_e32 v11, s9, v87
	v_fmac_f32_e32 v0, s10, v84
	v_fmac_f32_e32 v1, s10, v85
	v_fmac_f32_e32 v2, s10, v86
	v_fmac_f32_e32 v3, s10, v87
	global_load_dwordx4 v[84:87], v68, s[0:1] nt
	s_add_u32 s0, s0, 0x6000
	s_addc_u32 s1, s1, 0
	s_waitcnt vmcnt(15)
	v_readlane_b32 s8, v73, s2
	v_readlane_b32 s9, v74, s2
	v_readlane_b32 s10, v75, s2
	s_add_i32 s2, s2, 1
	v_fmac_f32_e32 v4, s8, v88
	v_fmac_f32_e32 v5, s8, v89
	v_fmac_f32_e32 v6, s8, v90
	v_fmac_f32_e32 v7, s8, v91
	v_fmac_f32_e32 v8, s9, v88
	v_fmac_f32_e32 v9, s9, v89
	v_fmac_f32_e32 v10, s9, v90
	v_fmac_f32_e32 v11, s9, v91
	v_fmac_f32_e32 v0, s10, v88
	v_fmac_f32_e32 v1, s10, v89
	v_fmac_f32_e32 v2, s10, v90
	v_fmac_f32_e32 v3, s10, v91
	global_load_dwordx4 v[88:91], v68, s[0:1] nt
	s_add_u32 s0, s0, 0x6000
	s_addc_u32 s1, s1, 0
	s_waitcnt vmcnt(15)
	v_readlane_b32 s8, v73, s2
	v_readlane_b32 s9, v74, s2
	v_readlane_b32 s10, v75, s2
	s_add_i32 s2, s2, 1
	v_fmac_f32_e32 v4, s8, v92
	v_fmac_f32_e32 v5, s8, v93
	v_fmac_f32_e32 v6, s8, v94
	v_fmac_f32_e32 v7, s8, v95
	v_fmac_f32_e32 v8, s9, v92
	v_fmac_f32_e32 v9, s9, v93
	v_fmac_f32_e32 v10, s9, v94
	v_fmac_f32_e32 v11, s9, v95
	v_fmac_f32_e32 v0, s10, v92
	v_fmac_f32_e32 v1, s10, v93
	v_fmac_f32_e32 v2, s10, v94
	v_fmac_f32_e32 v3, s10, v95
	global_load_dwordx4 v[92:95], v68, s[0:1] nt
	s_add_u32 s0, s0, 0x6000
	s_addc_u32 s1, s1, 0
	s_waitcnt vmcnt(15)
	v_readlane_b32 s8, v73, s2
	v_readlane_b32 s9, v74, s2
	v_readlane_b32 s10, v75, s2
	s_add_i32 s2, s2, 1
	v_fmac_f32_e32 v4, s8, v96
	v_fmac_f32_e32 v5, s8, v97
	v_fmac_f32_e32 v6, s8, v98
	v_fmac_f32_e32 v7, s8, v99
	v_fmac_f32_e32 v8, s9, v96
	v_fmac_f32_e32 v9, s9, v97
	v_fmac_f32_e32 v10, s9, v98
	v_fmac_f32_e32 v11, s9, v99
	v_fmac_f32_e32 v0, s10, v96
	v_fmac_f32_e32 v1, s10, v97
	v_fmac_f32_e32 v2, s10, v98
	v_fmac_f32_e32 v3, s10, v99
	global_load_dwordx4 v[96:99], v68, s[0:1] nt
	s_add_u32 s0, s0, 0x6000
	s_addc_u32 s1, s1, 0
	s_waitcnt vmcnt(15)
	v_readlane_b32 s8, v73, s2
	v_readlane_b32 s9, v74, s2
	v_readlane_b32 s10, v75, s2
	s_add_i32 s2, s2, 1
	v_fmac_f32_e32 v4, s8, v100
	v_fmac_f32_e32 v5, s8, v101
	v_fmac_f32_e32 v6, s8, v102
	v_fmac_f32_e32 v7, s8, v103
	v_fmac_f32_e32 v8, s9, v100
	v_fmac_f32_e32 v9, s9, v101
	v_fmac_f32_e32 v10, s9, v102
	v_fmac_f32_e32 v11, s9, v103
	v_fmac_f32_e32 v0, s10, v100
	v_fmac_f32_e32 v1, s10, v101
	v_fmac_f32_e32 v2, s10, v102
	v_fmac_f32_e32 v3, s10, v103
	global_load_dwordx4 v[100:103], v68, s[0:1] nt
	s_add_u32 s0, s0, 0x6000
	s_addc_u32 s1, s1, 0
	s_waitcnt vmcnt(15)
	v_readlane_b32 s8, v73, s2
	v_readlane_b32 s9, v74, s2
	v_readlane_b32 s10, v75, s2
	s_add_i32 s2, s2, 1
	v_fmac_f32_e32 v4, s8, v104
	v_fmac_f32_e32 v5, s8, v105
	v_fmac_f32_e32 v6, s8, v106
	v_fmac_f32_e32 v7, s8, v107
	v_fmac_f32_e32 v8, s9, v104
	v_fmac_f32_e32 v9, s9, v105
	v_fmac_f32_e32 v10, s9, v106
	v_fmac_f32_e32 v11, s9, v107
	v_fmac_f32_e32 v0, s10, v104
	v_fmac_f32_e32 v1, s10, v105
	v_fmac_f32_e32 v2, s10, v106
	v_fmac_f32_e32 v3, s10, v107
	global_load_dwordx4 v[104:107], v68, s[0:1] nt
	s_add_u32 s0, s0, 0x6000
	s_addc_u32 s1, s1, 0
	s_waitcnt vmcnt(15)
	v_readlane_b32 s8, v73, s2
	v_readlane_b32 s9, v74, s2
	v_readlane_b32 s10, v75, s2
	s_add_i32 s2, s2, 1
	v_fmac_f32_e32 v4, s8, v108
	v_fmac_f32_e32 v5, s8, v109
	v_fmac_f32_e32 v6, s8, v110
	v_fmac_f32_e32 v7, s8, v111
	v_fmac_f32_e32 v8, s9, v108
	v_fmac_f32_e32 v9, s9, v109
	v_fmac_f32_e32 v10, s9, v110
	v_fmac_f32_e32 v11, s9, v111
	v_fmac_f32_e32 v0, s10, v108
	v_fmac_f32_e32 v1, s10, v109
	v_fmac_f32_e32 v2, s10, v110
	v_fmac_f32_e32 v3, s10, v111
	global_load_dwordx4 v[108:111], v68, s[0:1] nt
	s_add_u32 s0, s0, 0x6000
	s_addc_u32 s1, s1, 0
	s_waitcnt vmcnt(15)
	v_readlane_b32 s8, v73, s2
	v_readlane_b32 s9, v74, s2
	v_readlane_b32 s10, v75, s2
	s_add_i32 s2, s2, 1
	v_fmac_f32_e32 v4, s8, v112
	v_fmac_f32_e32 v5, s8, v113
	v_fmac_f32_e32 v6, s8, v114
	v_fmac_f32_e32 v7, s8, v115
	v_fmac_f32_e32 v8, s9, v112
	v_fmac_f32_e32 v9, s9, v113
	v_fmac_f32_e32 v10, s9, v114
	v_fmac_f32_e32 v11, s9, v115
	v_fmac_f32_e32 v0, s10, v112
	v_fmac_f32_e32 v1, s10, v113
	v_fmac_f32_e32 v2, s10, v114
	v_fmac_f32_e32 v3, s10, v115
	global_load_dwordx4 v[112:115], v68, s[0:1] nt
	s_add_u32 s0, s0, 0x6000
	s_addc_u32 s1, s1, 0
	s_waitcnt vmcnt(15)
	v_readlane_b32 s8, v73, s2
	v_readlane_b32 s9, v74, s2
	v_readlane_b32 s10, v75, s2
	s_add_i32 s2, s2, 1
	v_fmac_f32_e32 v4, s8, v128
	v_fmac_f32_e32 v5, s8, v129
	v_fmac_f32_e32 v6, s8, v130
	v_fmac_f32_e32 v7, s8, v131
	v_fmac_f32_e32 v8, s9, v128
	v_fmac_f32_e32 v9, s9, v129
	v_fmac_f32_e32 v10, s9, v130
	v_fmac_f32_e32 v11, s9, v131
	v_fmac_f32_e32 v0, s10, v128
	v_fmac_f32_e32 v1, s10, v129
	v_fmac_f32_e32 v2, s10, v130
	v_fmac_f32_e32 v3, s10, v131
	global_load_dwordx4 v[128:131], v68, s[0:1] nt
	s_add_u32 s0, s0, 0x6000
	s_addc_u32 s1, s1, 0
	s_waitcnt vmcnt(15)
	v_readlane_b32 s8, v73, s2
	v_readlane_b32 s9, v74, s2
	v_readlane_b32 s10, v75, s2
	s_add_i32 s2, s2, 1
	v_fmac_f32_e32 v4, s8, v132
	v_fmac_f32_e32 v5, s8, v133
	v_fmac_f32_e32 v6, s8, v134
	v_fmac_f32_e32 v7, s8, v135
	v_fmac_f32_e32 v8, s9, v132
	v_fmac_f32_e32 v9, s9, v133
	v_fmac_f32_e32 v10, s9, v134
	v_fmac_f32_e32 v11, s9, v135
	v_fmac_f32_e32 v0, s10, v132
	v_fmac_f32_e32 v1, s10, v133
	v_fmac_f32_e32 v2, s10, v134
	v_fmac_f32_e32 v3, s10, v135
	global_load_dwordx4 v[132:135], v68, s[0:1] nt
	s_add_u32 s0, s0, 0x6000
	s_addc_u32 s1, s1, 0
	s_waitcnt vmcnt(15)
	v_readlane_b32 s8, v73, s2
	v_readlane_b32 s9, v74, s2
	v_readlane_b32 s10, v75, s2
	s_add_i32 s2, s2, 1
	v_fmac_f32_e32 v4, s8, v136
	v_fmac_f32_e32 v5, s8, v137
	v_fmac_f32_e32 v6, s8, v138
	v_fmac_f32_e32 v7, s8, v139
	v_fmac_f32_e32 v8, s9, v136
	v_fmac_f32_e32 v9, s9, v137
	v_fmac_f32_e32 v10, s9, v138
	v_fmac_f32_e32 v11, s9, v139
	v_fmac_f32_e32 v0, s10, v136
	v_fmac_f32_e32 v1, s10, v137
	v_fmac_f32_e32 v2, s10, v138
	v_fmac_f32_e32 v3, s10, v139
	global_load_dwordx4 v[136:139], v68, s[0:1] nt
	s_add_u32 s0, s0, 0x6000
	s_addc_u32 s1, s1, 0
	s_waitcnt vmcnt(15)
	v_readlane_b32 s8, v73, s2
	v_readlane_b32 s9, v74, s2
	v_readlane_b32 s10, v75, s2
	s_add_i32 s2, s2, 1
	v_fmac_f32_e32 v4, s8, v140
	v_fmac_f32_e32 v5, s8, v141
	v_fmac_f32_e32 v6, s8, v142
	v_fmac_f32_e32 v7, s8, v143
	v_fmac_f32_e32 v8, s9, v140
	v_fmac_f32_e32 v9, s9, v141
	v_fmac_f32_e32 v10, s9, v142
	v_fmac_f32_e32 v11, s9, v143
	v_fmac_f32_e32 v0, s10, v140
	v_fmac_f32_e32 v1, s10, v141
	v_fmac_f32_e32 v2, s10, v142
	v_fmac_f32_e32 v3, s10, v143
	global_load_dwordx4 v[140:143], v68, s[0:1] nt
	s_add_u32 s0, s0, 0x6000
	s_addc_u32 s1, s1, 0
	s_waitcnt vmcnt(15)
	v_readlane_b32 s8, v73, s2
	v_readlane_b32 s9, v74, s2
	v_readlane_b32 s10, v75, s2
	s_add_i32 s2, s2, 1
	v_fmac_f32_e32 v4, s8, v144
	v_fmac_f32_e32 v5, s8, v145
	v_fmac_f32_e32 v6, s8, v146
	v_fmac_f32_e32 v7, s8, v147
	v_fmac_f32_e32 v8, s9, v144
	v_fmac_f32_e32 v9, s9, v145
	v_fmac_f32_e32 v10, s9, v146
	v_fmac_f32_e32 v11, s9, v147
	v_fmac_f32_e32 v0, s10, v144
	v_fmac_f32_e32 v1, s10, v145
	v_fmac_f32_e32 v2, s10, v146
	v_fmac_f32_e32 v3, s10, v147
	global_load_dwordx4 v[144:147], v68, s[0:1] nt
	s_add_u32 s0, s0, 0x6000
	s_addc_u32 s1, s1, 0
	s_waitcnt vmcnt(15)
	v_readlane_b32 s8, v73, s2
	v_readlane_b32 s9, v74, s2
	v_readlane_b32 s10, v75, s2
	s_add_i32 s2, s2, 1
	v_fmac_f32_e32 v4, s8, v148
	v_fmac_f32_e32 v5, s8, v149
	v_fmac_f32_e32 v6, s8, v150
	v_fmac_f32_e32 v7, s8, v151
	v_fmac_f32_e32 v8, s9, v148
	v_fmac_f32_e32 v9, s9, v149
	v_fmac_f32_e32 v10, s9, v150
	v_fmac_f32_e32 v11, s9, v151
	v_fmac_f32_e32 v0, s10, v148
	v_fmac_f32_e32 v1, s10, v149
	v_fmac_f32_e32 v2, s10, v150
	v_fmac_f32_e32 v3, s10, v151
	global_load_dwordx4 v[148:151], v68, s[0:1] nt
	s_add_u32 s0, s0, 0x6000
	s_addc_u32 s1, s1, 0
	s_waitcnt vmcnt(15)
	v_readlane_b32 s8, v73, s2
	v_readlane_b32 s9, v74, s2
	v_readlane_b32 s10, v75, s2
	s_add_i32 s2, s2, 1
	v_fmac_f32_e32 v4, s8, v152
	v_fmac_f32_e32 v5, s8, v153
	v_fmac_f32_e32 v6, s8, v154
	v_fmac_f32_e32 v7, s8, v155
	v_fmac_f32_e32 v8, s9, v152
	v_fmac_f32_e32 v9, s9, v153
	v_fmac_f32_e32 v10, s9, v154
	v_fmac_f32_e32 v11, s9, v155
	v_fmac_f32_e32 v0, s10, v152
	v_fmac_f32_e32 v1, s10, v153
	v_fmac_f32_e32 v2, s10, v154
	v_fmac_f32_e32 v3, s10, v155
	global_load_dwordx4 v[152:155], v68, s[0:1] nt
	s_add_u32 s0, s0, 0x6000
	s_addc_u32 s1, s1, 0
	s_waitcnt vmcnt(15)
	v_readlane_b32 s8, v73, s2
	v_readlane_b32 s9, v74, s2
	v_readlane_b32 s10, v75, s2
	s_add_i32 s2, s2, 1
	v_fmac_f32_e32 v4, s8, v156
	v_fmac_f32_e32 v5, s8, v157
	v_fmac_f32_e32 v6, s8, v158
	v_fmac_f32_e32 v7, s8, v159
	v_fmac_f32_e32 v8, s9, v156
	v_fmac_f32_e32 v9, s9, v157
	v_fmac_f32_e32 v10, s9, v158
	v_fmac_f32_e32 v11, s9, v159
	v_fmac_f32_e32 v0, s10, v156
	v_fmac_f32_e32 v1, s10, v157
	v_fmac_f32_e32 v2, s10, v158
	v_fmac_f32_e32 v3, s10, v159
	global_load_dwordx4 v[156:159], v68, s[0:1] nt
	s_add_u32 s0, s0, 0x6000
	s_addc_u32 s1, s1, 0
	s_sub_i32 s3, s3, 1
	s_cmp_lg_u32 s3, 0
	s_cbranch_scc1 .Lada_loop
	s_waitcnt vmcnt(15)
	v_readlane_b32 s8, v73, s2
	v_readlane_b32 s9, v74, s2
	v_readlane_b32 s10, v75, s2
	s_add_i32 s2, s2, 1
	v_fmac_f32_e32 v4, s8, v84
	v_fmac_f32_e32 v5, s8, v85
	v_fmac_f32_e32 v6, s8, v86
	v_fmac_f32_e32 v7, s8, v87
	v_fmac_f32_e32 v8, s9, v84
	v_fmac_f32_e32 v9, s9, v85
	v_fmac_f32_e32 v10, s9, v86
	v_fmac_f32_e32 v11, s9, v87
	v_fmac_f32_e32 v0, s10, v84
	v_fmac_f32_e32 v1, s10, v85
	v_fmac_f32_e32 v2, s10, v86
	v_fmac_f32_e32 v3, s10, v87
	s_waitcnt vmcnt(14)
	v_readlane_b32 s8, v73, s2
	v_readlane_b32 s9, v74, s2
	v_readlane_b32 s10, v75, s2
	s_add_i32 s2, s2, 1
	v_fmac_f32_e32 v4, s8, v88
	v_fmac_f32_e32 v5, s8, v89
	v_fmac_f32_e32 v6, s8, v90
	v_fmac_f32_e32 v7, s8, v91
	v_fmac_f32_e32 v8, s9, v88
	v_fmac_f32_e32 v9, s9, v89
	v_fmac_f32_e32 v10, s9, v90
	v_fmac_f32_e32 v11, s9, v91
	v_fmac_f32_e32 v0, s10, v88
	v_fmac_f32_e32 v1, s10, v89
	v_fmac_f32_e32 v2, s10, v90
	v_fmac_f32_e32 v3, s10, v91
	s_waitcnt vmcnt(13)
	v_readlane_b32 s8, v73, s2
	v_readlane_b32 s9, v74, s2
	v_readlane_b32 s10, v75, s2
	s_add_i32 s2, s2, 1
	v_fmac_f32_e32 v4, s8, v92
	v_fmac_f32_e32 v5, s8, v93
	v_fmac_f32_e32 v6, s8, v94
	v_fmac_f32_e32 v7, s8, v95
	v_fmac_f32_e32 v8, s9, v92
	v_fmac_f32_e32 v9, s9, v93
	v_fmac_f32_e32 v10, s9, v94
	v_fmac_f32_e32 v11, s9, v95
	v_fmac_f32_e32 v0, s10, v92
	v_fmac_f32_e32 v1, s10, v93
	v_fmac_f32_e32 v2, s10, v94
	v_fmac_f32_e32 v3, s10, v95
	s_waitcnt vmcnt(12)
	v_readlane_b32 s8, v73, s2
	v_readlane_b32 s9, v74, s2
	v_readlane_b32 s10, v75, s2
	s_add_i32 s2, s2, 1
	v_fmac_f32_e32 v4, s8, v96
	v_fmac_f32_e32 v5, s8, v97
	v_fmac_f32_e32 v6, s8, v98
	v_fmac_f32_e32 v7, s8, v99
	v_fmac_f32_e32 v8, s9, v96
	v_fmac_f32_e32 v9, s9, v97
	v_fmac_f32_e32 v10, s9, v98
	v_fmac_f32_e32 v11, s9, v99
	v_fmac_f32_e32 v0, s10, v96
	v_fmac_f32_e32 v1, s10, v97
	v_fmac_f32_e32 v2, s10, v98
	v_fmac_f32_e32 v3, s10, v99
	s_waitcnt vmcnt(11)
	v_readlane_b32 s8, v73, s2
	v_readlane_b32 s9, v74, s2
	v_readlane_b32 s10, v75, s2
	s_add_i32 s2, s2, 1
	v_fmac_f32_e32 v4, s8, v100
	v_fmac_f32_e32 v5, s8, v101
	v_fmac_f32_e32 v6, s8, v102
	v_fmac_f32_e32 v7, s8, v103
	v_fmac_f32_e32 v8, s9, v100
	v_fmac_f32_e32 v9, s9, v101
	v_fmac_f32_e32 v10, s9, v102
	v_fmac_f32_e32 v11, s9, v103
	v_fmac_f32_e32 v0, s10, v100
	v_fmac_f32_e32 v1, s10, v101
	v_fmac_f32_e32 v2, s10, v102
	v_fmac_f32_e32 v3, s10, v103
	s_waitcnt vmcnt(10)
	v_readlane_b32 s8, v73, s2
	v_readlane_b32 s9, v74, s2
	v_readlane_b32 s10, v75, s2
	s_add_i32 s2, s2, 1
	v_fmac_f32_e32 v4, s8, v104
	v_fmac_f32_e32 v5, s8, v105
	v_fmac_f32_e32 v6, s8, v106
	v_fmac_f32_e32 v7, s8, v107
	v_fmac_f32_e32 v8, s9, v104
	v_fmac_f32_e32 v9, s9, v105
	v_fmac_f32_e32 v10, s9, v106
	v_fmac_f32_e32 v11, s9, v107
	v_fmac_f32_e32 v0, s10, v104
	v_fmac_f32_e32 v1, s10, v105
	v_fmac_f32_e32 v2, s10, v106
	v_fmac_f32_e32 v3, s10, v107
	s_waitcnt vmcnt(9)
	v_readlane_b32 s8, v73, s2
	v_readlane_b32 s9, v74, s2
	v_readlane_b32 s10, v75, s2
	s_add_i32 s2, s2, 1
	v_fmac_f32_e32 v4, s8, v108
	v_fmac_f32_e32 v5, s8, v109
	v_fmac_f32_e32 v6, s8, v110
	v_fmac_f32_e32 v7, s8, v111
	v_fmac_f32_e32 v8, s9, v108
	v_fmac_f32_e32 v9, s9, v109
	v_fmac_f32_e32 v10, s9, v110
	v_fmac_f32_e32 v11, s9, v111
	v_fmac_f32_e32 v0, s10, v108
	v_fmac_f32_e32 v1, s10, v109
	v_fmac_f32_e32 v2, s10, v110
	v_fmac_f32_e32 v3, s10, v111
	s_waitcnt vmcnt(8)
	v_readlane_b32 s8, v73, s2
	v_readlane_b32 s9, v74, s2
	v_readlane_b32 s10, v75, s2
	s_add_i32 s2, s2, 1
	v_fmac_f32_e32 v4, s8, v112
	v_fmac_f32_e32 v5, s8, v113
	v_fmac_f32_e32 v6, s8, v114
	v_fmac_f32_e32 v7, s8, v115
	v_fmac_f32_e32 v8, s9, v112
	v_fmac_f32_e32 v9, s9, v113
	v_fmac_f32_e32 v10, s9, v114
	v_fmac_f32_e32 v11, s9, v115
	v_fmac_f32_e32 v0, s10, v112
	v_fmac_f32_e32 v1, s10, v113
	v_fmac_f32_e32 v2, s10, v114
	v_fmac_f32_e32 v3, s10, v115
	s_waitcnt vmcnt(7)
	v_readlane_b32 s8, v73, s2
	v_readlane_b32 s9, v74, s2
	v_readlane_b32 s10, v75, s2
	s_add_i32 s2, s2, 1
	v_fmac_f32_e32 v4, s8, v128
	v_fmac_f32_e32 v5, s8, v129
	v_fmac_f32_e32 v6, s8, v130
	v_fmac_f32_e32 v7, s8, v131
	v_fmac_f32_e32 v8, s9, v128
	v_fmac_f32_e32 v9, s9, v129
	v_fmac_f32_e32 v10, s9, v130
	v_fmac_f32_e32 v11, s9, v131
	v_fmac_f32_e32 v0, s10, v128
	v_fmac_f32_e32 v1, s10, v129
	v_fmac_f32_e32 v2, s10, v130
	v_fmac_f32_e32 v3, s10, v131
	s_waitcnt vmcnt(6)
	v_readlane_b32 s8, v73, s2
	v_readlane_b32 s9, v74, s2
	v_readlane_b32 s10, v75, s2
	s_add_i32 s2, s2, 1
	v_fmac_f32_e32 v4, s8, v132
	v_fmac_f32_e32 v5, s8, v133
	v_fmac_f32_e32 v6, s8, v134
	v_fmac_f32_e32 v7, s8, v135
	v_fmac_f32_e32 v8, s9, v132
	v_fmac_f32_e32 v9, s9, v133
	v_fmac_f32_e32 v10, s9, v134
	v_fmac_f32_e32 v11, s9, v135
	v_fmac_f32_e32 v0, s10, v132
	v_fmac_f32_e32 v1, s10, v133
	v_fmac_f32_e32 v2, s10, v134
	v_fmac_f32_e32 v3, s10, v135
	s_waitcnt vmcnt(5)
	v_readlane_b32 s8, v73, s2
	v_readlane_b32 s9, v74, s2
	v_readlane_b32 s10, v75, s2
	s_add_i32 s2, s2, 1
	v_fmac_f32_e32 v4, s8, v136
	v_fmac_f32_e32 v5, s8, v137
	v_fmac_f32_e32 v6, s8, v138
	v_fmac_f32_e32 v7, s8, v139
	v_fmac_f32_e32 v8, s9, v136
	v_fmac_f32_e32 v9, s9, v137
	v_fmac_f32_e32 v10, s9, v138
	v_fmac_f32_e32 v11, s9, v139
	v_fmac_f32_e32 v0, s10, v136
	v_fmac_f32_e32 v1, s10, v137
	v_fmac_f32_e32 v2, s10, v138
	v_fmac_f32_e32 v3, s10, v139
	s_waitcnt vmcnt(4)
	v_readlane_b32 s8, v73, s2
	v_readlane_b32 s9, v74, s2
	v_readlane_b32 s10, v75, s2
	s_add_i32 s2, s2, 1
	v_fmac_f32_e32 v4, s8, v140
	v_fmac_f32_e32 v5, s8, v141
	v_fmac_f32_e32 v6, s8, v142
	v_fmac_f32_e32 v7, s8, v143
	v_fmac_f32_e32 v8, s9, v140
	v_fmac_f32_e32 v9, s9, v141
	v_fmac_f32_e32 v10, s9, v142
	v_fmac_f32_e32 v11, s9, v143
	v_fmac_f32_e32 v0, s10, v140
	v_fmac_f32_e32 v1, s10, v141
	v_fmac_f32_e32 v2, s10, v142
	v_fmac_f32_e32 v3, s10, v143
	s_waitcnt vmcnt(3)
	v_readlane_b32 s8, v73, s2
	v_readlane_b32 s9, v74, s2
	v_readlane_b32 s10, v75, s2
	s_add_i32 s2, s2, 1
	v_fmac_f32_e32 v4, s8, v144
	v_fmac_f32_e32 v5, s8, v145
	v_fmac_f32_e32 v6, s8, v146
	v_fmac_f32_e32 v7, s8, v147
	v_fmac_f32_e32 v8, s9, v144
	v_fmac_f32_e32 v9, s9, v145
	v_fmac_f32_e32 v10, s9, v146
	v_fmac_f32_e32 v11, s9, v147
	v_fmac_f32_e32 v0, s10, v144
	v_fmac_f32_e32 v1, s10, v145
	v_fmac_f32_e32 v2, s10, v146
	v_fmac_f32_e32 v3, s10, v147
	s_waitcnt vmcnt(2)
	v_readlane_b32 s8, v73, s2
	v_readlane_b32 s9, v74, s2
	v_readlane_b32 s10, v75, s2
	s_add_i32 s2, s2, 1
	v_fmac_f32_e32 v4, s8, v148
	v_fmac_f32_e32 v5, s8, v149
	v_fmac_f32_e32 v6, s8, v150
	v_fmac_f32_e32 v7, s8, v151
	v_fmac_f32_e32 v8, s9, v148
	v_fmac_f32_e32 v9, s9, v149
	v_fmac_f32_e32 v10, s9, v150
	v_fmac_f32_e32 v11, s9, v151
	v_fmac_f32_e32 v0, s10, v148
	v_fmac_f32_e32 v1, s10, v149
	v_fmac_f32_e32 v2, s10, v150
	v_fmac_f32_e32 v3, s10, v151
	s_waitcnt vmcnt(1)
	v_readlane_b32 s8, v73, s2
	v_readlane_b32 s9, v74, s2
	v_readlane_b32 s10, v75, s2
	s_add_i32 s2, s2, 1
	v_fmac_f32_e32 v4, s8, v152
	v_fmac_f32_e32 v5, s8, v153
	v_fmac_f32_e32 v6, s8, v154
	v_fmac_f32_e32 v7, s8, v155
	v_fmac_f32_e32 v8, s9, v152
	v_fmac_f32_e32 v9, s9, v153
	v_fmac_f32_e32 v10, s9, v154
	v_fmac_f32_e32 v11, s9, v155
	v_fmac_f32_e32 v0, s10, v152
	v_fmac_f32_e32 v1, s10, v153
	v_fmac_f32_e32 v2, s10, v154
	v_fmac_f32_e32 v3, s10, v155
	s_waitcnt vmcnt(0)
	v_readlane_b32 s8, v73, s2
	v_readlane_b32 s9, v74, s2
	v_readlane_b32 s10, v75, s2
	s_add_i32 s2, s2, 1
	v_fmac_f32_e32 v4, s8, v156
	v_fmac_f32_e32 v5, s8, v157
	v_fmac_f32_e32 v6, s8, v158
	v_fmac_f32_e32 v7, s8, v159
	v_fmac_f32_e32 v8, s9, v156
	v_fmac_f32_e32 v9, s9, v157
	v_fmac_f32_e32 v10, s9, v158
	v_fmac_f32_e32 v11, s9, v159
	v_fmac_f32_e32 v0, s10, v156
	v_fmac_f32_e32 v1, s10, v157
	v_fmac_f32_e32 v2, s10, v158
	v_fmac_f32_e32 v3, s10, v159
	v_and_b32_e32 v12, 15, v37
	v_readlane_b32 s8, v254, 9
	v_lshl_or_b32 v12, v54, 4, v12
	v_readlane_b32 s10, v254, 11
	v_readlane_b32 s11, v254, 12
	v_lshl_add_u32 v14, v12, 1, v12
	v_readlane_b32 s9, v254, 10
	v_mov_b64_e32 v[12:13], s[10:11]
	v_mad_i64_i32 v[12:13], s[0:1], v14, s67, v[12:13]
	v_lshl_add_u64 v[12:13], v[40:41], 2, v[12:13]
	global_store_dwordx4 v[12:13], v[4:7], off
	v_readlane_b32 s12, v254, 13
	v_readlane_b32 s13, v254, 14
	v_add_co_u32_e32 v4, vcc, 0x6000, v12
	v_readlane_b32 s14, v254, 15
	s_nop 0
	v_addc_co_u32_e32 v5, vcc, 0, v13, vcc
	global_store_dwordx4 v[4:5], v[8:11], off
	v_add_co_u32_e32 v4, vcc, 0xc000, v12
	v_readlane_b32 s15, v254, 16
	s_nop 0
	v_addc_co_u32_e32 v5, vcc, 0, v13, vcc
	v_readlane_b32 s16, v254, 17
	v_readlane_b32 s17, v254, 18
	v_readlane_b32 s18, v254, 19
	v_readlane_b32 s19, v254, 20
	v_readlane_b32 s20, v254, 21
	v_readlane_b32 s21, v254, 22
	v_readlane_b32 s22, v254, 23
	v_readlane_b32 s23, v254, 24
	global_store_dwordx4 v[4:5], v[0:3], off
	s_branch .LBB0_582
